# GDN state scan rewritten: 3-deep register ring fed by plain global loads (no LDS-DMA ring / ds_read / m0 traffic), same per-step arithmetic
# speedup vs baseline: 1.0076x; 1.0046x over previous
; #define LAS __attribute__((address_space(3)))
; DI f32x16 zero16() { f32x16 z; for (int i = 0; i < 16; ++i) z[i] = 0.f; return z; }
; DI void phase_scan(KArgs args, LAS unsigned char* L, const Ctx& c) {
;     ...
;     const int nwu = c.nseq * 24, wu = c.bid;
;     if (wu < nwu && c.wave == 0) {
;         const int lane = c.lane;
;         const int chain = wu >> 1, nt = wu & 1, seq = chain / 12, rem = chain % 12, head = rem >> 1, dir = rem & 1;
;         const int nch = c.seqlen >> 6, gch0 = seq * nch;
;         unsigned char* GS = BIGP(unsigned char, B_GSCR);
;         f32x16 S[2]; S[0] = zero16(); S[1] = zero16();
;         bf16x8 A[2][2][4]; u32x4 cm[2][2][2];
;         const long gstep = (long)(dir ? -1 : 1) * 12 * GSTRIDE;
;         const unsigned char* G0 = GS + (size_t)(((gch0 + (dir ? nch - 1 : 0)) * 6 + head) * 2 + dir) * GSTRIDE;
;         unsigned char* Gs = (unsigned char*)G0;
;         float glv[4];
; #pragma unroll
;         for (int q = 0; q < 4; ++q) { const int sq = q * 64 + lane; glv[q] = *(const float*)(G0 + (long)(sq < nch ? sq : nch - 1) * gstep + 40960); }
;         LAS unsigned char* RING = L + 81920;
;         int dslot = 0, rslot = 0, dstage = 0;
;     ...
;         SCAN_DMA(); SCAN_DMA(); SCAN_DMA(); SCAN_DMA(); SCAN_DMA();
;         asm volatile("s_waitcnt vmcnt(48)" ::: "memory"); SCAN_LOAD(0);
.LBB0_646:
	s_movk_i32 s33, 0x600
	s_and_b64 vcc, exec, s[0:1]
	s_cbranch_vccz .LBB0_946
	v_readlane_b32 s2, v254, 23
	s_lshr_b32 s30, s60, 6
	v_readlane_b32 s3, v254, 24
	s_and_b64 s[0:1], s[2:3], exec
	s_cselect_b32 s0, 6, 8
	s_add_i32 s31, s30, -1
	v_writelane_b32 v254, s0, 32
	s_and_b64 s[0:1], s[2:3], exec
	s_cselect_b32 s2, 0xc0, 24
	s_cmp_lt_u32 s61, 64
	s_cselect_b64 s[0:1], -1, 0
	s_cmp_lt_i32 s68, s2
	s_cselect_b64 s[2:3], -1, 0
	s_and_b64 s[0:1], s[2:3], s[0:1]
	s_andn2_b64 vcc, exec, s[0:1]
	s_movk_i32 s27, 0x90
	v_readlane_b32 s28, v254, 27
	v_readlane_b32 s29, v254, 29
	s_cbranch_vccnz .LBB0_651
	s_setprio 3
	s_ashr_i32 s0, s68, 1
	s_mul_hi_i32 s1, s0, 0x2aaaaaab
	s_lshr_b32 s2, s1, 31
	s_ashr_i32 s1, s1, 1
	s_add_i32 s1, s1, s2
	s_mul_i32 s2, s1, 12
	s_sub_i32 s2, s0, s2
	v_readlane_b32 s4, v254, 32
	s_bfe_i32 s3, s2, 0x10000
	s_and_b32 s0, s2, 1
	s_lshl_b32 s4, s1, s4
	s_cmp_eq_u32 s0, 0
	s_mov_b32 s0, 0x78c00
	s_cselect_b32 s1, 0, -1
	s_cselect_b32 s0, s0, 0xfff87400
	s_and_b32 s3, s3, s31
	s_add_i32 s3, s3, s4
	s_mul_i32 s3, s3, 12
	s_add_i32 s24, s3, s2
	s_mul_hi_i32 s23, s24, 0xa100
	s_mul_i32 s24, s24, 0xa100
	s_waitcnt lgkmcnt(0)
	s_add_u32 s6, s72, s24
	s_addc_u32 s7, s73, s23
	s_add_u32 s2, s6, 0x37800000
	s_addc_u32 s3, s7, 0
	v_min_i32_e32 v1, s31, v28
	v_mov_b64_e32 v[4:5], s[2:3]
	v_mad_u64_u32 v[6:7], s[4:5], s0, v1, v[4:5]
	v_mad_i32_i24 v1, s1, v1, v7
	v_or_b32_e32 v7, 64, v28
	v_min_i32_e32 v2, s31, v7
	v_mad_u64_u32 v[8:9], s[4:5], s0, v2, v[4:5]
	v_or_b32_e32 v12, 0x80, v28
	v_mad_i32_i24 v9, s1, v2, v9
	v_min_i32_e32 v2, s31, v12
	v_mad_u64_u32 v[10:11], s[4:5], s0, v2, v[4:5]
	v_or_b32_e32 v13, 0xc0, v28
	v_mad_i32_i24 v11, s1, v2, v11
	v_min_i32_e32 v2, s31, v13
	v_mad_u64_u32 v[4:5], s[4:5], s0, v2, v[4:5]
	s_add_u32 s20, s6, 0x37802000
	s_addc_u32 s21, s7, 0
	s_lshl_b32 s4, s68, 12
	s_and_b32 s25, s4, 0x1000
	s_add_u32 s18, s2, s0
	s_addc_u32 s19, s3, s1
	s_add_u32 s16, s18, 0x2000
	s_addc_u32 s17, s19, 0
	s_add_u32 s14, s18, s0
	s_addc_u32 s15, s19, s1
	s_add_u32 s12, s14, 0x2000
	s_addc_u32 s13, s15, 0
	s_add_u32 s10, s14, s0
	s_addc_u32 s11, s15, s1
	s_mov_b32 s26, 0xa000
	s_add_u32 s8, s10, 0x2000
	v_add_co_u32_e32 v6, vcc, s26, v6
	v_lshlrev_b32_e32 v148, 4, v7
	s_addc_u32 s9, s11, 0
	v_addc_co_u32_e32 v7, vcc, 0, v1, vcc
	s_add_u32 s6, s10, s0
	v_add_co_u32_e32 v8, vcc, s26, v8
	s_addc_u32 s7, s11, s1
	s_nop 0
	v_addc_co_u32_e32 v9, vcc, 0, v9, vcc
	s_add_u32 s4, s6, 0x2000
	v_add_co_u32_e32 v10, vcc, s26, v10
	s_addc_u32 s5, s7, 0
	s_add_i32 s22, 0, 0x14000
	v_addc_co_u32_e32 v11, vcc, 0, v11, vcc
	v_mad_i32_i24 v5, s1, v2, v5
	v_lshlrev_b32_e32 v2, 4, v28
	v_add_co_u32_e32 v4, vcc, s26, v4
	v_addc_co_u32_e32 v5, vcc, 0, v5, vcc
	global_load_dword v1, v[6:7], off
	global_load_dword v168, v[8:9], off
	global_load_dword v169, v[10:11], off
	global_load_dword v170, v[4:5], off
	v_lshlrev_b32_e32 v150, 4, v12
	v_lshlrev_b32_e32 v152, 4, v13
	v_or_b32_e32 v154, 0x1000, v2
	v_or_b32_e32 v156, 0x1400, v2
	v_or_b32_e32 v158, 0x1800, v2
	v_or_b32_e32 v160, 0x1c00, v2
	v_lshl_or_b32 v162, v28, 5, s25
	v_mov_b32_e32 v163, v3
	v_lshl_add_u64 v[12:13], s[20:21], 0, v[162:163]
	v_lshl_add_u64 v[12:13], v[12:13], 0, 16
	v_or_b32_e32 v164, 0x800, v162
	v_mov_b32_e32 v165, v3
	v_lshl_add_u64 v[14:15], s[20:21], 0, v[164:165]
	v_lshl_add_u64 v[14:15], v[14:15], 0, 16
	v_lshl_add_u64 v[16:17], s[16:17], 0, v[162:163]
	v_lshl_add_u64 v[16:17], v[16:17], 0, 16
	v_lshl_add_u64 v[18:19], s[16:17], 0, v[164:165]
	v_lshl_add_u64 v[18:19], v[18:19], 0, 16
	v_lshl_add_u64 v[20:21], s[12:13], 0, v[162:163]
	v_lshl_add_u64 v[20:21], v[20:21], 0, 16
	v_lshl_add_u64 v[22:23], s[12:13], 0, v[164:165]
	v_lshl_add_u64 v[22:23], v[22:23], 0, 16
	v_lshl_add_u64 v[24:25], s[8:9], 0, v[162:163]
	v_lshl_add_u64 v[24:25], v[24:25], 0, 16
	v_lshl_add_u64 v[26:27], s[8:9], 0, v[164:165]
	v_lshl_add_u64 v[26:27], v[26:27], 0, 16
	v_lshl_add_u64 v[28:29], s[4:5], 0, v[162:163]
	v_lshl_add_u64 v[28:29], v[28:29], 0, 16
	v_lshl_add_u64 v[30:31], s[4:5], 0, v[164:165]
	v_lshl_add_u64 v[30:31], v[30:31], 0, 16
	s_add_u32 s4, s24, s25
	s_addc_u32 s5, s23, 0
	s_add_u32 s4, s72, s4
	s_addc_u32 s5, s73, s5
	v_lshl_add_u64 v[4:5], s[4:5], 0, v[2:3]
	s_mov_b64 s[4:5], 0x37808800
	v_lshl_add_u64 v[166:167], v[4:5], 0, s[4:5]
	v_mov_b32_e32 v4, 0
	v_mov_b32_e32 v149, v3
	v_mov_b32_e32 v151, v3
	v_mov_b32_e32 v153, v3
	v_mov_b32_e32 v155, v3
	v_mov_b32_e32 v157, v3
	v_mov_b32_e32 v159, v3
	v_mov_b32_e32 v161, v3
	s_lshl_b64 s[8:9], s[0:1], 1
	v_mov_b32_e32 v5, v4
	v_mov_b32_e32 v6, v4
	v_mov_b32_e32 v7, v4
	v_mov_b32_e32 v8, v4
	v_mov_b32_e32 v9, v4
	v_mov_b32_e32 v10, v4
	v_mov_b32_e32 v11, v4
	v_mov_b32_e32 v12, v4
	v_mov_b32_e32 v13, v4
	v_mov_b32_e32 v14, v4
	v_mov_b32_e32 v15, v4
	v_mov_b32_e32 v16, v4
	v_mov_b32_e32 v17, v4
	v_mov_b32_e32 v18, v4
	v_mov_b32_e32 v19, v4
	v_mov_b32_e32 v20, v4
	v_mov_b32_e32 v21, v4
	v_mov_b32_e32 v22, v4
	v_mov_b32_e32 v23, v4
	v_mov_b32_e32 v24, v4
	v_mov_b32_e32 v25, v4
	v_mov_b32_e32 v26, v4
	v_mov_b32_e32 v27, v4
	v_mov_b32_e32 v28, v4
	v_mov_b32_e32 v29, v4
	v_mov_b32_e32 v30, v4
	v_mov_b32_e32 v31, v4
	v_mov_b32_e32 v32, v4
	v_mov_b32_e32 v33, v4
	v_mov_b32_e32 v34, v4
	v_mov_b32_e32 v35, v4
	s_mov_b64 s[12:13], s[2:3]
	s_mov_b32 s11, 0
	s_mov_b32 s10, 0
	s_add_u32 s14, s12, 0x1000
	s_addc_u32 s15, s13, 0
	s_add_u32 s16, s12, 0x2000
	s_addc_u32 s17, s13, 0
	global_load_dwordx4 v[36:39], v2, s[12:13]
	global_load_dwordx4 v[40:43], v2, s[12:13] offset:1024
	global_load_dwordx4 v[44:47], v2, s[12:13] offset:2048
	global_load_dwordx4 v[48:51], v2, s[12:13] offset:3072
	global_load_dwordx4 v[52:55], v2, s[14:15]
; DI void phase_scan(KArgs args, LAS unsigned char* L, const Ctx& c) {
;     ...
;         SCAN_DMA(); SCAN_DMA(); SCAN_DMA(); SCAN_DMA(); SCAN_DMA();
;         asm volatile("s_waitcnt vmcnt(48)" ::: "memory"); SCAN_LOAD(0);
;         asm volatile("s_waitcnt vmcnt(36)" ::: "memory"); SCAN_LOAD(1);
;         for (int step = 0; step < nch; step += 2) {
;             SCAN_STEP(0, step);     asm volatile("s_waitcnt vmcnt(24)" ::: "memory"); SCAN_LOAD(0); SCAN_DMA();
;             SCAN_STEP(1, step + 1); asm volatile("s_waitcnt vmcnt(24)" ::: "memory"); SCAN_LOAD(1); SCAN_DMA();
	global_load_dwordx4 v[56:59], v2, s[14:15] offset:1024
	global_load_dwordx4 v[60:63], v2, s[14:15] offset:2048
	global_load_dwordx4 v[64:67], v2, s[14:15] offset:3072
	global_load_dwordx4 v[68:71], v162, s[16:17]
	global_load_dwordx4 v[72:75], v162, s[16:17] offset:16
	global_load_dwordx4 v[76:79], v164, s[16:17]
	global_load_dwordx4 v[80:83], v164, s[16:17] offset:16
	s_add_i32 s11, s11, 1
	s_cmp_le_u32 s11, s31
	s_cselect_b32 s6, s0, 0
	s_cselect_b32 s7, s1, 0
	s_add_u32 s12, s12, s6
	s_addc_u32 s13, s13, s7
	s_add_u32 s14, s12, 0x1000
	s_addc_u32 s15, s13, 0
	s_add_u32 s16, s12, 0x2000
	s_addc_u32 s17, s13, 0
	global_load_dwordx4 v[84:87], v2, s[12:13]
	global_load_dwordx4 v[88:91], v2, s[12:13] offset:1024
	global_load_dwordx4 v[92:95], v2, s[12:13] offset:2048
	global_load_dwordx4 v[96:99], v2, s[12:13] offset:3072
	global_load_dwordx4 v[100:103], v2, s[14:15]
	global_load_dwordx4 v[104:107], v2, s[14:15] offset:1024
	global_load_dwordx4 v[108:111], v2, s[14:15] offset:2048
	global_load_dwordx4 v[112:115], v2, s[14:15] offset:3072
	global_load_dwordx4 v[116:119], v162, s[16:17]
	global_load_dwordx4 v[120:123], v162, s[16:17] offset:16
	global_load_dwordx4 v[124:127], v164, s[16:17]
	global_load_dwordx4 v[128:131], v164, s[16:17] offset:16
	s_add_i32 s11, s11, 1
	s_cmp_le_u32 s11, s31
	s_cselect_b32 s6, s0, 0
	s_cselect_b32 s7, s1, 0
	s_add_u32 s12, s12, s6
	s_addc_u32 s13, s13, s7
	s_add_u32 s14, s12, 0x1000
	s_addc_u32 s15, s13, 0
	s_add_u32 s16, s12, 0x2000
	s_addc_u32 s17, s13, 0
	global_load_dwordx4 v[178:181], v2, s[12:13]
	global_load_dwordx4 v[182:185], v2, s[12:13] offset:1024
	global_load_dwordx4 v[186:189], v2, s[12:13] offset:2048
	global_load_dwordx4 v[190:193], v2, s[12:13] offset:3072
	global_load_dwordx4 v[194:197], v2, s[14:15]
	global_load_dwordx4 v[198:201], v2, s[14:15] offset:1024
	global_load_dwordx4 v[202:205], v2, s[14:15] offset:2048
	global_load_dwordx4 v[226:229], v2, s[14:15] offset:3072
	global_load_dwordx4 v[230:233], v162, s[16:17]
	global_load_dwordx4 v[234:237], v162, s[16:17] offset:16
	global_load_dwordx4 v[238:241], v164, s[16:17]
	global_load_dwordx4 v[242:245], v164, s[16:17] offset:16
	s_add_i32 s11, s11, 1
	s_cmp_le_u32 s11, s31
	s_cselect_b32 s6, s0, 0
	s_cselect_b32 s7, s1, 0
	s_add_u32 s12, s12, s6
	s_addc_u32 s13, s13, s7
	s_waitcnt vmcnt(12)
.Lscan_loop:
	s_waitcnt vmcnt(32)
	s_lshr_b32 s6, s10, 6
	s_cmp_lt_u32 s10, 64
	s_cselect_b64 vcc, -1, 0
	s_cmp_eq_u32 s6, 1
	s_cselect_b64 s[4:5], -1, 0
	s_cmp_eq_u32 s6, 2
	s_cselect_b64 s[6:7], -1, 0
	v_cndmask_b32_e64 v172, v170, v169, s[6:7]
	v_cndmask_b32_e64 v172, v172, v168, s[4:5]
	v_cndmask_b32_e32 v172, v172, v1, vcc
	v_cvt_pk_bf16_f32 v132, v4, v5
	v_cvt_pk_bf16_f32 v133, v6, v7
	v_cvt_pk_bf16_f32 v134, v8, v9
	v_cvt_pk_bf16_f32 v135, v10, v11
	v_cvt_pk_bf16_f32 v136, v12, v13
	v_cvt_pk_bf16_f32 v137, v14, v15
	v_cvt_pk_bf16_f32 v138, v16, v17
	v_cvt_pk_bf16_f32 v139, v18, v19
	v_cvt_pk_bf16_f32 v140, v20, v21
	v_cvt_pk_bf16_f32 v141, v22, v23
	v_cvt_pk_bf16_f32 v142, v24, v25
	v_cvt_pk_bf16_f32 v143, v26, v27
	v_cvt_pk_bf16_f32 v144, v28, v29
	v_cvt_pk_bf16_f32 v145, v30, v31
	v_cvt_pk_bf16_f32 v146, v32, v33
	v_cvt_pk_bf16_f32 v147, v34, v35
	v_readlane_b32 s4, v172, s10
	global_store_dwordx4 v[166:167], v[132:135], off offset:-2048
	global_store_dwordx4 v[166:167], v[136:139], off offset:-1024
	global_store_dwordx4 v[166:167], v[140:143], off
	global_store_dwordx4 v[166:167], v[144:147], off offset:1024
	v_lshlrev_b32_e32 v174, 16, v68
	v_and_b32_e32 v175, 0xffff0000, v68
	v_pk_fma_f32 v[4:5], v[4:5], s[4:5], v[174:175] op_sel_hi:[1,0,1]
	v_lshlrev_b32_e32 v174, 16, v69
	v_and_b32_e32 v175, 0xffff0000, v69
	v_pk_fma_f32 v[6:7], v[6:7], s[4:5], v[174:175] op_sel_hi:[1,0,1]
	v_lshlrev_b32_e32 v174, 16, v70
	v_and_b32_e32 v175, 0xffff0000, v70
	v_pk_fma_f32 v[8:9], v[8:9], s[4:5], v[174:175] op_sel_hi:[1,0,1]
	v_lshlrev_b32_e32 v174, 16, v71
	v_and_b32_e32 v175, 0xffff0000, v71
	v_pk_fma_f32 v[10:11], v[10:11], s[4:5], v[174:175] op_sel_hi:[1,0,1]
	v_lshlrev_b32_e32 v174, 16, v72
	v_and_b32_e32 v175, 0xffff0000, v72
	v_pk_fma_f32 v[12:13], v[12:13], s[4:5], v[174:175] op_sel_hi:[1,0,1]
	v_lshlrev_b32_e32 v174, 16, v73
	v_and_b32_e32 v175, 0xffff0000, v73
	v_pk_fma_f32 v[14:15], v[14:15], s[4:5], v[174:175] op_sel_hi:[1,0,1]
	v_lshlrev_b32_e32 v174, 16, v74
	v_and_b32_e32 v175, 0xffff0000, v74
	v_pk_fma_f32 v[16:17], v[16:17], s[4:5], v[174:175] op_sel_hi:[1,0,1]
	v_lshlrev_b32_e32 v174, 16, v75
	v_and_b32_e32 v175, 0xffff0000, v75
	v_pk_fma_f32 v[18:19], v[18:19], s[4:5], v[174:175] op_sel_hi:[1,0,1]
	v_lshlrev_b32_e32 v174, 16, v76
	v_and_b32_e32 v175, 0xffff0000, v76
	v_pk_fma_f32 v[20:21], v[20:21], s[4:5], v[174:175] op_sel_hi:[1,0,1]
	v_lshlrev_b32_e32 v174, 16, v77
	v_and_b32_e32 v175, 0xffff0000, v77
	v_pk_fma_f32 v[22:23], v[22:23], s[4:5], v[174:175] op_sel_hi:[1,0,1]
	v_lshlrev_b32_e32 v174, 16, v78
	v_and_b32_e32 v175, 0xffff0000, v78
	v_pk_fma_f32 v[24:25], v[24:25], s[4:5], v[174:175] op_sel_hi:[1,0,1]
	v_lshlrev_b32_e32 v174, 16, v79
	v_and_b32_e32 v175, 0xffff0000, v79
	v_pk_fma_f32 v[26:27], v[26:27], s[4:5], v[174:175] op_sel_hi:[1,0,1]
	v_lshlrev_b32_e32 v174, 16, v80
	v_and_b32_e32 v175, 0xffff0000, v80
	v_pk_fma_f32 v[28:29], v[28:29], s[4:5], v[174:175] op_sel_hi:[1,0,1]
	v_lshlrev_b32_e32 v174, 16, v81
	v_and_b32_e32 v175, 0xffff0000, v81
	v_pk_fma_f32 v[30:31], v[30:31], s[4:5], v[174:175] op_sel_hi:[1,0,1]
	v_lshlrev_b32_e32 v174, 16, v82
	v_and_b32_e32 v175, 0xffff0000, v82
	v_pk_fma_f32 v[32:33], v[32:33], s[4:5], v[174:175] op_sel_hi:[1,0,1]
	v_lshlrev_b32_e32 v174, 16, v83
	v_and_b32_e32 v175, 0xffff0000, v83
; DI void phase_scan(KArgs args, LAS unsigned char* L, const Ctx& c) {
;     ...
;         SCAN_DMA(); SCAN_DMA(); SCAN_DMA(); SCAN_DMA(); SCAN_DMA();
;         asm volatile("s_waitcnt vmcnt(48)" ::: "memory"); SCAN_LOAD(0);
;         asm volatile("s_waitcnt vmcnt(36)" ::: "memory"); SCAN_LOAD(1);
;         for (int step = 0; step < nch; step += 2) {
;             SCAN_STEP(0, step);     asm volatile("s_waitcnt vmcnt(24)" ::: "memory"); SCAN_LOAD(0); SCAN_DMA();
;             SCAN_STEP(1, step + 1); asm volatile("s_waitcnt vmcnt(24)" ::: "memory"); SCAN_LOAD(1); SCAN_DMA();
	v_pk_fma_f32 v[34:35], v[34:35], s[4:5], v[174:175] op_sel_hi:[1,0,1]
	s_nop 1
	v_mfma_f32_32x32x16_bf16 v[4:19], v[36:39], v[132:135], v[4:19]
	v_mfma_f32_32x32x16_bf16 v[20:35], v[52:55], v[132:135], v[20:35]
	v_mfma_f32_32x32x16_bf16 v[4:19], v[40:43], v[136:139], v[4:19]
	v_mfma_f32_32x32x16_bf16 v[20:35], v[56:59], v[136:139], v[20:35]
	v_mfma_f32_32x32x16_bf16 v[4:19], v[44:47], v[140:143], v[4:19]
	v_mfma_f32_32x32x16_bf16 v[20:35], v[60:63], v[140:143], v[20:35]
	v_mfma_f32_32x32x16_bf16 v[4:19], v[48:51], v[144:147], v[4:19]
	v_mfma_f32_32x32x16_bf16 v[20:35], v[64:67], v[144:147], v[20:35]
	v_lshl_add_u64 v[166:167], v[166:167], 0, s[0:1]
	s_add_u32 s14, s12, 0x1000
	s_addc_u32 s15, s13, 0
	s_add_u32 s16, s12, 0x2000
	s_addc_u32 s17, s13, 0
	global_load_dwordx4 v[36:39], v2, s[12:13]
	global_load_dwordx4 v[40:43], v2, s[12:13] offset:1024
	global_load_dwordx4 v[44:47], v2, s[12:13] offset:2048
	global_load_dwordx4 v[48:51], v2, s[12:13] offset:3072
	global_load_dwordx4 v[52:55], v2, s[14:15]
	global_load_dwordx4 v[56:59], v2, s[14:15] offset:1024
	global_load_dwordx4 v[60:63], v2, s[14:15] offset:2048
	global_load_dwordx4 v[64:67], v2, s[14:15] offset:3072
	global_load_dwordx4 v[68:71], v162, s[16:17]
	global_load_dwordx4 v[72:75], v162, s[16:17] offset:16
	global_load_dwordx4 v[76:79], v164, s[16:17]
	global_load_dwordx4 v[80:83], v164, s[16:17] offset:16
	s_add_i32 s11, s11, 1
	s_cmp_le_u32 s11, s31
	s_cselect_b32 s6, s0, 0
	s_cselect_b32 s7, s1, 0
	s_add_u32 s12, s12, s6
	s_addc_u32 s13, s13, s7
	s_add_i32 s10, s10, 1
	s_cmp_ge_u32 s10, s30
	s_cbranch_scc1 .Lscan_exit
	s_waitcnt vmcnt(32)
	s_lshr_b32 s6, s10, 6
	s_cmp_lt_u32 s10, 64
	s_cselect_b64 vcc, -1, 0
	s_cmp_eq_u32 s6, 1
	s_cselect_b64 s[4:5], -1, 0
	s_cmp_eq_u32 s6, 2
	s_cselect_b64 s[6:7], -1, 0
	v_cndmask_b32_e64 v172, v170, v169, s[6:7]
	v_cndmask_b32_e64 v172, v172, v168, s[4:5]
	v_cndmask_b32_e32 v172, v172, v1, vcc
	v_cvt_pk_bf16_f32 v132, v4, v5
	v_cvt_pk_bf16_f32 v133, v6, v7
	v_cvt_pk_bf16_f32 v134, v8, v9
	v_cvt_pk_bf16_f32 v135, v10, v11
	v_cvt_pk_bf16_f32 v136, v12, v13
	v_cvt_pk_bf16_f32 v137, v14, v15
	v_cvt_pk_bf16_f32 v138, v16, v17
	v_cvt_pk_bf16_f32 v139, v18, v19
	v_cvt_pk_bf16_f32 v140, v20, v21
	v_cvt_pk_bf16_f32 v141, v22, v23
	v_cvt_pk_bf16_f32 v142, v24, v25
	v_cvt_pk_bf16_f32 v143, v26, v27
	v_cvt_pk_bf16_f32 v144, v28, v29
	v_cvt_pk_bf16_f32 v145, v30, v31
	v_cvt_pk_bf16_f32 v146, v32, v33
	v_cvt_pk_bf16_f32 v147, v34, v35
	v_readlane_b32 s4, v172, s10
	global_store_dwordx4 v[166:167], v[132:135], off offset:-2048
	global_store_dwordx4 v[166:167], v[136:139], off offset:-1024
	global_store_dwordx4 v[166:167], v[140:143], off
	global_store_dwordx4 v[166:167], v[144:147], off offset:1024
	v_lshlrev_b32_e32 v174, 16, v116
	v_and_b32_e32 v175, 0xffff0000, v116
	v_pk_fma_f32 v[4:5], v[4:5], s[4:5], v[174:175] op_sel_hi:[1,0,1]
	v_lshlrev_b32_e32 v174, 16, v117
	v_and_b32_e32 v175, 0xffff0000, v117
	v_pk_fma_f32 v[6:7], v[6:7], s[4:5], v[174:175] op_sel_hi:[1,0,1]
	v_lshlrev_b32_e32 v174, 16, v118
	v_and_b32_e32 v175, 0xffff0000, v118
	v_pk_fma_f32 v[8:9], v[8:9], s[4:5], v[174:175] op_sel_hi:[1,0,1]
	v_lshlrev_b32_e32 v174, 16, v119
	v_and_b32_e32 v175, 0xffff0000, v119
	v_pk_fma_f32 v[10:11], v[10:11], s[4:5], v[174:175] op_sel_hi:[1,0,1]
	v_lshlrev_b32_e32 v174, 16, v120
	v_and_b32_e32 v175, 0xffff0000, v120
	v_pk_fma_f32 v[12:13], v[12:13], s[4:5], v[174:175] op_sel_hi:[1,0,1]
	v_lshlrev_b32_e32 v174, 16, v121
	v_and_b32_e32 v175, 0xffff0000, v121
	v_pk_fma_f32 v[14:15], v[14:15], s[4:5], v[174:175] op_sel_hi:[1,0,1]
	v_lshlrev_b32_e32 v174, 16, v122
	v_and_b32_e32 v175, 0xffff0000, v122
	v_pk_fma_f32 v[16:17], v[16:17], s[4:5], v[174:175] op_sel_hi:[1,0,1]
	v_lshlrev_b32_e32 v174, 16, v123
	v_and_b32_e32 v175, 0xffff0000, v123
	v_pk_fma_f32 v[18:19], v[18:19], s[4:5], v[174:175] op_sel_hi:[1,0,1]
	v_lshlrev_b32_e32 v174, 16, v124
	v_and_b32_e32 v175, 0xffff0000, v124
	v_pk_fma_f32 v[20:21], v[20:21], s[4:5], v[174:175] op_sel_hi:[1,0,1]
	v_lshlrev_b32_e32 v174, 16, v125
	v_and_b32_e32 v175, 0xffff0000, v125
	v_pk_fma_f32 v[22:23], v[22:23], s[4:5], v[174:175] op_sel_hi:[1,0,1]
	v_lshlrev_b32_e32 v174, 16, v126
	v_and_b32_e32 v175, 0xffff0000, v126
	v_pk_fma_f32 v[24:25], v[24:25], s[4:5], v[174:175] op_sel_hi:[1,0,1]
	v_lshlrev_b32_e32 v174, 16, v127
	v_and_b32_e32 v175, 0xffff0000, v127
	v_pk_fma_f32 v[26:27], v[26:27], s[4:5], v[174:175] op_sel_hi:[1,0,1]
	v_lshlrev_b32_e32 v174, 16, v128
	v_and_b32_e32 v175, 0xffff0000, v128
	v_pk_fma_f32 v[28:29], v[28:29], s[4:5], v[174:175] op_sel_hi:[1,0,1]
	v_lshlrev_b32_e32 v174, 16, v129
	v_and_b32_e32 v175, 0xffff0000, v129
	v_pk_fma_f32 v[30:31], v[30:31], s[4:5], v[174:175] op_sel_hi:[1,0,1]
	v_lshlrev_b32_e32 v174, 16, v130
	v_and_b32_e32 v175, 0xffff0000, v130
	v_pk_fma_f32 v[32:33], v[32:33], s[4:5], v[174:175] op_sel_hi:[1,0,1]
	v_lshlrev_b32_e32 v174, 16, v131
	v_and_b32_e32 v175, 0xffff0000, v131
	v_pk_fma_f32 v[34:35], v[34:35], s[4:5], v[174:175] op_sel_hi:[1,0,1]
	s_nop 1
	v_mfma_f32_32x32x16_bf16 v[4:19], v[84:87], v[132:135], v[4:19]
	v_mfma_f32_32x32x16_bf16 v[20:35], v[100:103], v[132:135], v[20:35]
	v_mfma_f32_32x32x16_bf16 v[4:19], v[88:91], v[136:139], v[4:19]
	v_mfma_f32_32x32x16_bf16 v[20:35], v[104:107], v[136:139], v[20:35]
	v_mfma_f32_32x32x16_bf16 v[4:19], v[92:95], v[140:143], v[4:19]
	v_mfma_f32_32x32x16_bf16 v[20:35], v[108:111], v[140:143], v[20:35]
	v_mfma_f32_32x32x16_bf16 v[4:19], v[96:99], v[144:147], v[4:19]
	v_mfma_f32_32x32x16_bf16 v[20:35], v[112:115], v[144:147], v[20:35]
	v_lshl_add_u64 v[166:167], v[166:167], 0, s[0:1]
	s_add_u32 s14, s12, 0x1000
	s_addc_u32 s15, s13, 0
	s_add_u32 s16, s12, 0x2000
	s_addc_u32 s17, s13, 0
	global_load_dwordx4 v[84:87], v2, s[12:13]
	global_load_dwordx4 v[88:91], v2, s[12:13] offset:1024
	global_load_dwordx4 v[92:95], v2, s[12:13] offset:2048
	global_load_dwordx4 v[96:99], v2, s[12:13] offset:3072
	global_load_dwordx4 v[100:103], v2, s[14:15]
	global_load_dwordx4 v[104:107], v2, s[14:15] offset:1024
	global_load_dwordx4 v[108:111], v2, s[14:15] offset:2048
	global_load_dwordx4 v[112:115], v2, s[14:15] offset:3072
	global_load_dwordx4 v[116:119], v162, s[16:17]
	global_load_dwordx4 v[120:123], v162, s[16:17] offset:16
	global_load_dwordx4 v[124:127], v164, s[16:17]
	global_load_dwordx4 v[128:131], v164, s[16:17] offset:16
	s_add_i32 s11, s11, 1
	s_cmp_le_u32 s11, s31
	s_cselect_b32 s6, s0, 0
	s_cselect_b32 s7, s1, 0
	s_add_u32 s12, s12, s6
	s_addc_u32 s13, s13, s7
	s_add_i32 s10, s10, 1
	s_cmp_ge_u32 s10, s30
	s_cbranch_scc1 .Lscan_exit
; DI void phase_scan(KArgs args, LAS unsigned char* L, const Ctx& c) {
;     ...
;         SCAN_DMA(); SCAN_DMA(); SCAN_DMA(); SCAN_DMA(); SCAN_DMA();
;         asm volatile("s_waitcnt vmcnt(48)" ::: "memory"); SCAN_LOAD(0);
;         asm volatile("s_waitcnt vmcnt(36)" ::: "memory"); SCAN_LOAD(1);
;         for (int step = 0; step < nch; step += 2) {
;             SCAN_STEP(0, step);     asm volatile("s_waitcnt vmcnt(24)" ::: "memory"); SCAN_LOAD(0); SCAN_DMA();
;             SCAN_STEP(1, step + 1); asm volatile("s_waitcnt vmcnt(24)" ::: "memory"); SCAN_LOAD(1); SCAN_DMA();
;         }
;         asm volatile("s_waitcnt vmcnt(0)" ::: "memory");
	s_waitcnt vmcnt(32)
	s_lshr_b32 s6, s10, 6
	s_cmp_lt_u32 s10, 64
	s_cselect_b64 vcc, -1, 0
	s_cmp_eq_u32 s6, 1
	s_cselect_b64 s[4:5], -1, 0
	s_cmp_eq_u32 s6, 2
	s_cselect_b64 s[6:7], -1, 0
	v_cndmask_b32_e64 v172, v170, v169, s[6:7]
	v_cndmask_b32_e64 v172, v172, v168, s[4:5]
	v_cndmask_b32_e32 v172, v172, v1, vcc
	v_cvt_pk_bf16_f32 v132, v4, v5
	v_cvt_pk_bf16_f32 v133, v6, v7
	v_cvt_pk_bf16_f32 v134, v8, v9
	v_cvt_pk_bf16_f32 v135, v10, v11
	v_cvt_pk_bf16_f32 v136, v12, v13
	v_cvt_pk_bf16_f32 v137, v14, v15
	v_cvt_pk_bf16_f32 v138, v16, v17
	v_cvt_pk_bf16_f32 v139, v18, v19
	v_cvt_pk_bf16_f32 v140, v20, v21
	v_cvt_pk_bf16_f32 v141, v22, v23
	v_cvt_pk_bf16_f32 v142, v24, v25
	v_cvt_pk_bf16_f32 v143, v26, v27
	v_cvt_pk_bf16_f32 v144, v28, v29
	v_cvt_pk_bf16_f32 v145, v30, v31
	v_cvt_pk_bf16_f32 v146, v32, v33
	v_cvt_pk_bf16_f32 v147, v34, v35
	v_readlane_b32 s4, v172, s10
	global_store_dwordx4 v[166:167], v[132:135], off offset:-2048
	global_store_dwordx4 v[166:167], v[136:139], off offset:-1024
	global_store_dwordx4 v[166:167], v[140:143], off
	global_store_dwordx4 v[166:167], v[144:147], off offset:1024
	v_lshlrev_b32_e32 v174, 16, v230
	v_and_b32_e32 v175, 0xffff0000, v230
	v_pk_fma_f32 v[4:5], v[4:5], s[4:5], v[174:175] op_sel_hi:[1,0,1]
	v_lshlrev_b32_e32 v174, 16, v231
	v_and_b32_e32 v175, 0xffff0000, v231
	v_pk_fma_f32 v[6:7], v[6:7], s[4:5], v[174:175] op_sel_hi:[1,0,1]
	v_lshlrev_b32_e32 v174, 16, v232
	v_and_b32_e32 v175, 0xffff0000, v232
	v_pk_fma_f32 v[8:9], v[8:9], s[4:5], v[174:175] op_sel_hi:[1,0,1]
	v_lshlrev_b32_e32 v174, 16, v233
	v_and_b32_e32 v175, 0xffff0000, v233
	v_pk_fma_f32 v[10:11], v[10:11], s[4:5], v[174:175] op_sel_hi:[1,0,1]
	v_lshlrev_b32_e32 v174, 16, v234
	v_and_b32_e32 v175, 0xffff0000, v234
	v_pk_fma_f32 v[12:13], v[12:13], s[4:5], v[174:175] op_sel_hi:[1,0,1]
	v_lshlrev_b32_e32 v174, 16, v235
	v_and_b32_e32 v175, 0xffff0000, v235
	v_pk_fma_f32 v[14:15], v[14:15], s[4:5], v[174:175] op_sel_hi:[1,0,1]
	v_lshlrev_b32_e32 v174, 16, v236
	v_and_b32_e32 v175, 0xffff0000, v236
	v_pk_fma_f32 v[16:17], v[16:17], s[4:5], v[174:175] op_sel_hi:[1,0,1]
	v_lshlrev_b32_e32 v174, 16, v237
	v_and_b32_e32 v175, 0xffff0000, v237
	v_pk_fma_f32 v[18:19], v[18:19], s[4:5], v[174:175] op_sel_hi:[1,0,1]
	v_lshlrev_b32_e32 v174, 16, v238
	v_and_b32_e32 v175, 0xffff0000, v238
	v_pk_fma_f32 v[20:21], v[20:21], s[4:5], v[174:175] op_sel_hi:[1,0,1]
	v_lshlrev_b32_e32 v174, 16, v239
	v_and_b32_e32 v175, 0xffff0000, v239
	v_pk_fma_f32 v[22:23], v[22:23], s[4:5], v[174:175] op_sel_hi:[1,0,1]
	v_lshlrev_b32_e32 v174, 16, v240
	v_and_b32_e32 v175, 0xffff0000, v240
	v_pk_fma_f32 v[24:25], v[24:25], s[4:5], v[174:175] op_sel_hi:[1,0,1]
	v_lshlrev_b32_e32 v174, 16, v241
	v_and_b32_e32 v175, 0xffff0000, v241
	v_pk_fma_f32 v[26:27], v[26:27], s[4:5], v[174:175] op_sel_hi:[1,0,1]
	v_lshlrev_b32_e32 v174, 16, v242
	v_and_b32_e32 v175, 0xffff0000, v242
	v_pk_fma_f32 v[28:29], v[28:29], s[4:5], v[174:175] op_sel_hi:[1,0,1]
	v_lshlrev_b32_e32 v174, 16, v243
	v_and_b32_e32 v175, 0xffff0000, v243
	v_pk_fma_f32 v[30:31], v[30:31], s[4:5], v[174:175] op_sel_hi:[1,0,1]
	v_lshlrev_b32_e32 v174, 16, v244
	v_and_b32_e32 v175, 0xffff0000, v244
	v_pk_fma_f32 v[32:33], v[32:33], s[4:5], v[174:175] op_sel_hi:[1,0,1]
	v_lshlrev_b32_e32 v174, 16, v245
	v_and_b32_e32 v175, 0xffff0000, v245
	v_pk_fma_f32 v[34:35], v[34:35], s[4:5], v[174:175] op_sel_hi:[1,0,1]
	s_nop 1
	v_mfma_f32_32x32x16_bf16 v[4:19], v[178:181], v[132:135], v[4:19]
	v_mfma_f32_32x32x16_bf16 v[20:35], v[194:197], v[132:135], v[20:35]
	v_mfma_f32_32x32x16_bf16 v[4:19], v[182:185], v[136:139], v[4:19]
	v_mfma_f32_32x32x16_bf16 v[20:35], v[198:201], v[136:139], v[20:35]
	v_mfma_f32_32x32x16_bf16 v[4:19], v[186:189], v[140:143], v[4:19]
	v_mfma_f32_32x32x16_bf16 v[20:35], v[202:205], v[140:143], v[20:35]
	v_mfma_f32_32x32x16_bf16 v[4:19], v[190:193], v[144:147], v[4:19]
	v_mfma_f32_32x32x16_bf16 v[20:35], v[226:229], v[144:147], v[20:35]
	v_lshl_add_u64 v[166:167], v[166:167], 0, s[0:1]
	s_add_u32 s14, s12, 0x1000
	s_addc_u32 s15, s13, 0
	s_add_u32 s16, s12, 0x2000
	s_addc_u32 s17, s13, 0
	global_load_dwordx4 v[178:181], v2, s[12:13]
	global_load_dwordx4 v[182:185], v2, s[12:13] offset:1024
	global_load_dwordx4 v[186:189], v2, s[12:13] offset:2048
	global_load_dwordx4 v[190:193], v2, s[12:13] offset:3072
	global_load_dwordx4 v[194:197], v2, s[14:15]
	global_load_dwordx4 v[198:201], v2, s[14:15] offset:1024
	global_load_dwordx4 v[202:205], v2, s[14:15] offset:2048
	global_load_dwordx4 v[226:229], v2, s[14:15] offset:3072
	global_load_dwordx4 v[230:233], v162, s[16:17]
	global_load_dwordx4 v[234:237], v162, s[16:17] offset:16
	global_load_dwordx4 v[238:241], v164, s[16:17]
	global_load_dwordx4 v[242:245], v164, s[16:17] offset:16
	s_add_i32 s11, s11, 1
	s_cmp_le_u32 s11, s31
	s_cselect_b32 s6, s0, 0
	s_cselect_b32 s7, s1, 0
	s_add_u32 s12, s12, s6
	s_addc_u32 s13, s13, s7
	s_add_i32 s10, s10, 1
	s_cmp_ge_u32 s10, s30
	s_cbranch_scc1 .Lscan_exit
	s_branch .Lscan_loop
.Lscan_exit:
	s_waitcnt vmcnt(0)
	s_setprio 0
